# prep section B: sigmoid 1/(1+exp(-y)) IEEE-division expansion replaced by v_rcp_f32 (f32, 1 ulp), the dead chain instructions turned into s_nop
# speedup vs baseline: 1.0510x; 1.0151x over previous
.LBB0_316:
	v_ashrrev_i32_e32 v181, 3, v135
	s_lshr_b32 s0, s23, 7
	v_and_b32_e32 v183, -2, v181
	v_and_b32_e32 v1, 15, v135
	s_lshl_b32 s0, s0, 6
	v_add3_u32 v60, s7, -3, v183
	v_lshlrev_b32_e32 v3, 3, v1
	s_and_b32 s0, s0, 0x180
	v_max_i32_e32 v16, -2, v60
	v_add_u32_e32 v62, s7, v183
	v_or_b32_e32 v61, s0, v3
	v_add_u32_e32 v16, 2, v16
	v_mov_b32_e32 v17, v0
	v_max_i32_e32 v20, 0, v62
	v_mov_b32_e32 v21, v0
	v_lshlrev_b32_e32 v28, 1, v61
	v_mov_b32_e32 v29, v0
	v_max_i32_e32 v12, -1, v60
	v_lshl_add_u64 v[16:17], s[4:5], 0, v[16:17]
	v_lshl_add_u64 v[20:21], s[4:5], 0, v[20:21]
	v_max_i32_e32 v26, -4, v60
	v_lshl_add_u64 v[24:25], s[12:13], 0, v[28:29]
	v_max_i32_e32 v8, 0, v60
	v_mov_b32_e32 v9, v0
	v_add_u32_e32 v12, 1, v12
	v_mov_b32_e32 v13, v0
	v_lshlrev_b64 v[36:37], 12, v[16:17]
	v_lshlrev_b64 v[40:41], 12, v[20:21]
	v_add_u32_e32 v26, 4, v26
	v_mov_b32_e32 v27, v0
	v_lshl_add_u64 v[8:9], s[4:5], 0, v[8:9]
	v_lshl_add_u64 v[12:13], s[4:5], 0, v[12:13]
	v_lshl_add_u64 v[16:17], v[24:25], 0, v[36:37]
	v_lshl_add_u64 v[20:21], v[24:25], 0, v[40:41]
	v_lshl_add_u64 v[26:27], s[4:5], 0, v[26:27]
	s_waitcnt lgkmcnt(0)
	s_barrier
	v_lshlrev_b64 v[30:31], 12, v[8:9]
	v_lshlrev_b64 v[32:33], 12, v[12:13]
	global_load_dwordx4 v[16:19], v[16:17], off
	v_lshlrev_b64 v[44:45], 12, v[26:27]
	global_load_dwordx4 v[20:23], v[20:21], off
	v_lshl_add_u64 v[8:9], v[24:25], 0, v[30:31]
	v_lshl_add_u64 v[12:13], v[24:25], 0, v[32:33]
	v_lshl_add_u64 v[24:25], v[24:25], 0, v[44:45]
	global_load_dwordx4 v[24:27], v[24:25], off
	v_mov_b32_e32 v47, v0
	global_load_dwordx4 v[8:11], v[8:9], off
	v_or_b32_e32 v46, 0x400, v28
	global_load_dwordx4 v[12:15], v[12:13], off
	v_lshl_add_u64 v[54:55], s[12:13], 0, v[40:41]
	v_lshl_add_u64 v[40:41], v[54:55], 0, v[46:47]
	v_lshl_add_u64 v[58:59], s[12:13], 0, v[44:45]
	v_lshl_add_u64 v[48:49], s[12:13], 0, v[30:31]
	v_lshl_add_u64 v[50:51], s[12:13], 0, v[32:33]
	v_lshl_add_u64 v[52:53], s[12:13], 0, v[36:37]
	global_load_dwordx4 v[40:43], v[40:41], off
	v_lshl_add_u64 v[44:45], v[58:59], 0, v[46:47]
	v_lshl_add_u64 v[28:29], v[48:49], 0, v[46:47]
	v_lshl_add_u64 v[32:33], v[50:51], 0, v[46:47]
	v_lshl_add_u64 v[36:37], v[52:53], 0, v[46:47]
	global_load_dwordx4 v[44:47], v[44:45], off
	v_cmp_gt_i32_e64 s[4:5], 0, v62
	v_readlane_b32 s34, v251, 51
	v_lshl_or_b32 v3, s6, 7, v3
	v_readlane_b32 s35, v251, 52
	v_or_b32_e32 v3, 0x400, v3
	v_cmp_gt_i32_e64 s[6:7], -4, v60
	global_load_dwordx4 v[28:31], v[28:29], off
	v_mov_b32_e32 v57, v0
	v_lshlrev_b32_e32 v56, 1, v3
	v_lshl_add_u64 v[48:49], v[48:49], 0, v[56:57]
	v_cmp_gt_i32_e32 vcc, 0, v60
	v_cmp_gt_i32_e64 s[0:1], -1, v60
	v_cmp_gt_i32_e64 s[2:3], -2, v60
	s_movk_i32 s25, 0x4000
	global_load_dwordx4 v[32:35], v[32:33], off
	v_lshl_add_u64 v[50:51], v[50:51], 0, v[56:57]
	global_load_dwordx4 v[36:39], v[36:37], off
	s_nop 0
	global_load_dwordx4 v[104:107], v[48:49], off
	global_load_dwordx4 v[108:111], v[50:51], off
	s_mov_b64 s[28:29], 0x2000
	s_movk_i32 s26, 0x6000
	s_mov_b64 s[30:31], 0x6000
	v_add_u32_e32 v201, 64, v2
	v_lshlrev_b32_e32 v197, 4, v1
	v_lshrrev_b32_e32 v198, 5, v135
	v_bfe_u32 v200, v135, 2, 2
	s_waitcnt vmcnt(11)
	v_cndmask_b32_e64 v161, v16, 0, s[2:3]
	v_cndmask_b32_e64 v129, v17, 0, s[2:3]
	s_waitcnt vmcnt(10)
	v_cndmask_b32_e64 v163, v20, 0, s[4:5]
	v_cndmask_b32_e64 v131, v21, 0, s[4:5]
	v_lshlrev_b32_e32 v20, 2, v61
	v_mov_b32_e32 v21, v0
	v_cndmask_b32_e64 v125, v22, 0, s[4:5]
	v_cndmask_b32_e64 v117, v23, 0, s[4:5]
	v_lshl_add_u64 v[22:23], s[34:35], 0, v[20:21]
	s_waitcnt vmcnt(9)
	v_cndmask_b32_e64 v202, v26, 0, s[6:7]
	v_add_co_u32_e64 v26, s[8:9], s62, v22
	v_cndmask_b32_e64 v203, v27, 0, s[6:7]
	s_nop 0
	v_addc_co_u32_e64 v27, s[8:9], 0, v23, s[8:9]
	s_waitcnt vmcnt(8)
	v_cndmask_b32_e64 v165, v8, 0, vcc
	v_cndmask_b32_e64 v118, v9, 0, vcc
	s_waitcnt vmcnt(7)
	v_cndmask_b32_e64 v133, v12, 0, s[0:1]
	v_cndmask_b32_e64 v127, v13, 0, s[0:1]
	v_lshl_add_u64 v[8:9], v[52:53], 0, v[56:57]
	v_lshl_add_u64 v[12:13], v[54:55], 0, v[56:57]
	v_lshl_add_u64 v[16:17], v[58:59], 0, v[56:57]
	v_add_co_u32_e64 v48, s[8:9], s25, v22
	v_cndmask_b32_e64 v119, v10, 0, vcc
	v_cndmask_b32_e64 v120, v11, 0, vcc
	v_cndmask_b32_e64 v121, v14, 0, s[0:1]
	v_cndmask_b32_e64 v113, v15, 0, s[0:1]
	v_cndmask_b32_e64 v123, v18, 0, s[2:3]
	v_cndmask_b32_e64 v115, v19, 0, s[2:3]
	global_load_dwordx4 v[8:11], v[8:9], off
	v_cndmask_b32_e64 v196, v24, 0, s[6:7]
	global_load_dwordx4 v[12:15], v[12:13], off
	v_cndmask_b32_e64 v199, v25, 0, s[6:7]
	global_load_dwordx4 v[16:19], v[16:17], off
	s_nop 0
	global_load_dwordx4 v[72:75], v20, s[34:35]
	global_load_dwordx4 v[88:91], v20, s[34:35] offset:16
	v_lshl_add_u64 v[24:25], v[22:23], 0, s[28:29]
	v_addc_co_u32_e64 v49, s[8:9], 0, v23, s[8:9]
	global_load_dwordx4 v[76:79], v[26:27], off
	global_load_dwordx4 v[92:95], v[24:25], off offset:16
	v_lshl_add_u64 v[24:25], v[22:23], 0, s[48:49]
	v_add_co_u32_e64 v52, s[8:9], s26, v22
	global_load_dwordx4 v[96:99], v[24:25], off offset:16
	s_nop 0
	v_addc_co_u32_e64 v53, s[8:9], 0, v23, s[8:9]
	v_lshl_add_u64 v[24:25], v[22:23], 0, s[30:31]
	global_load_dwordx4 v[80:83], v[52:53], off
	global_load_dwordx4 v[100:103], v[24:25], off offset:16
	s_mov_b64 s[8:9], 0x2800
	s_waitcnt vmcnt(16)
	v_cndmask_b32_e64 v180, v40, 0, s[4:5]
	v_cndmask_b32_e64 v187, v41, 0, s[4:5]
	v_cndmask_b32_e64 v191, v42, 0, s[4:5]
	v_cndmask_b32_e64 v195, v43, 0, s[4:5]
	global_load_dwordx4 v[40:43], v20, s[34:35] offset:2048
	global_load_dwordx4 v[56:59], v20, s[34:35] offset:2064
	v_lshl_add_u64 v[20:21], v[22:23], 0, s[8:9]
	s_mov_b64 s[8:9], 0x4800
	s_waitcnt vmcnt(17)
	v_cndmask_b32_e64 v172, v44, 0, s[6:7]
	v_cndmask_b32_e64 v174, v45, 0, s[6:7]
	v_cndmask_b32_e64 v175, v46, 0, s[6:7]
	v_cndmask_b32_e64 v176, v47, 0, s[6:7]
	global_load_dwordx4 v[44:47], v[26:27], off offset:2048
	v_lshl_add_u64 v[24:25], v[22:23], 0, s[8:9]
	global_load_dwordx4 v[84:87], v[48:49], off
	s_nop 0
	global_load_dwordx4 v[48:51], v[48:49], off offset:2048
	s_nop 0
	global_load_dwordx4 v[64:67], v[20:21], off offset:16
	global_load_dwordx4 v[68:71], v[24:25], off offset:16
	s_waitcnt vmcnt(18)
	v_cndmask_b32_e64 v148, v105, 0, vcc
	v_cndmask_b32_e64 v168, v104, 0, vcc
	v_lshlrev_b32_e32 v104, 16, v120
	v_and_b32_e32 v105, 0xffff0000, v120
	v_lshlrev_b32_e32 v112, 16, v113
	v_and_b32_e32 v113, 0xffff0000, v113
	v_lshlrev_b32_e32 v114, 16, v115
	v_and_b32_e32 v115, 0xffff0000, v115
	v_lshlrev_b32_e32 v116, 16, v117
	v_and_b32_e32 v117, 0xffff0000, v117
	s_mov_b64 s[8:9], 0x6800
	v_cndmask_b32_e64 v140, v107, 0, vcc
	v_lshl_add_u64 v[20:21], v[22:23], 0, s[8:9]
	v_cndmask_b32_e64 v144, v106, 0, vcc
	global_load_dwordx4 v[52:55], v[52:53], off offset:2048
	s_nop 0
	global_load_dwordx4 v[60:63], v[20:21], off offset:16
	v_cndmask_b32_e64 v177, v28, 0, vcc
	v_cndmask_b32_e64 v184, v29, 0, vcc
	v_cndmask_b32_e64 v188, v30, 0, vcc
	v_cndmask_b32_e64 v192, v31, 0, vcc
	v_cndmask_b32_e64 v178, v32, 0, s[0:1]
	v_cndmask_b32_e64 v185, v33, 0, s[0:1]
	v_cndmask_b32_e64 v189, v34, 0, s[0:1]
	v_cndmask_b32_e64 v193, v35, 0, s[0:1]
	s_waitcnt vmcnt(19)
	v_cndmask_b32_e64 v141, v111, 0, s[0:1]
	v_cndmask_b32_e64 v145, v110, 0, s[0:1]
	v_cndmask_b32_e64 v149, v109, 0, s[0:1]
	v_cndmask_b32_e64 v169, v108, 0, s[0:1]
	v_xor_b32_e32 v108, 1, v182
	v_lshlrev_b32_e32 v120, 16, v121
	v_and_b32_e32 v121, 0xffff0000, v121
	v_lshlrev_b32_e32 v122, 16, v123
	v_and_b32_e32 v123, 0xffff0000, v123
	v_lshlrev_b32_e32 v124, 16, v125
	v_and_b32_e32 v125, 0xffff0000, v125
	v_lshlrev_b32_e32 v130, 16, v131
	v_and_b32_e32 v131, 0xffff0000, v131
	v_cndmask_b32_e64 v179, v36, 0, s[2:3]
	v_cndmask_b32_e64 v186, v37, 0, s[2:3]
	v_cndmask_b32_e64 v190, v38, 0, s[2:3]
	v_cndmask_b32_e64 v194, v39, 0, s[2:3]
	s_waitcnt vmcnt(18)
	v_cndmask_b32_e64 v142, v11, 0, s[2:3]
	v_cndmask_b32_e64 v146, v10, 0, s[2:3]
	s_waitcnt vmcnt(17)
	v_cndmask_b32_e64 v171, v12, 0, s[4:5]
	v_lshlrev_b32_e32 v12, 2, v3
	v_cndmask_b32_e64 v151, v13, 0, s[4:5]
	s_waitcnt vmcnt(14)
	v_pk_fma_f32 v[104:105], v[90:91], v[104:105], 0 op_sel_hi:[1,1,0]
	v_mov_b32_e32 v13, v0
	v_lshl_add_u64 v[20:21], s[34:35], 0, v[12:13]
	v_cndmask_b32_e64 v147, v14, 0, s[4:5]
	s_waitcnt vmcnt(12)
	v_pk_fma_f32 v[104:105], v[94:95], v[112:113], v[104:105]
	v_add_co_u32_e32 v14, vcc, s62, v20
	v_cndmask_b32_e64 v143, v15, 0, s[4:5]
	s_waitcnt vmcnt(11)
	v_pk_fma_f32 v[104:105], v[98:99], v[114:115], v[104:105]
	v_addc_co_u32_e32 v15, vcc, 0, v21, vcc
	v_cndmask_b32_e64 v137, v18, 0, s[6:7]
	s_waitcnt vmcnt(9)
	v_pk_fma_f32 v[104:105], v[102:103], v[116:117], v[104:105]
	v_add_co_u32_e32 v18, vcc, s25, v20
	v_mul_f32_e32 v3, 0xbfb8aa3b, v105
	v_exp_f32_e32 v107, v3
	v_mul_f32_e32 v3, 0xbfb8aa3b, v104
	v_exp_f32_e32 v106, v3
	v_cndmask_b32_e64 v136, v19, 0, s[6:7]
	v_addc_co_u32_e32 v19, vcc, 0, v21, vcc
	v_pk_add_f32 v[2:3], v[106:107], 1.0 op_sel_hi:[1,0]
	v_cndmask_b32_e64 v150, v9, 0, s[2:3]
	s_nop 0
	v_cndmask_b32_e64 v170, v8, 0, s[2:3]
	v_cndmask_b32_e64 v138, v17, 0, s[6:7]
	v_cndmask_b32_e64 v139, v16, 0, s[6:7]
	global_load_dwordx4 v[8:11], v12, s[34:35] offset:16
	global_load_dwordx4 v[24:27], v12, s[34:35]
	v_lshl_add_u64 v[12:13], v[20:21], 0, s[28:29]
	v_lshl_add_u64 v[16:17], v[20:21], 0, s[48:49]
	v_lshl_add_u64 v[22:23], v[20:21], 0, s[30:31]
	v_add_co_u32_e32 v20, vcc, s26, v20
	s_nop 0
	s_nop 0
	v_addc_co_u32_e32 v21, vcc, 0, v21, vcc
	v_cmp_lt_i32_e32 vcc, v108, v201
	v_pk_fma_f32 v[90:91], v[90:91], v[112:113], 0 op_sel_hi:[1,1,0]
	s_mov_b32 s4, 0x358637bd
	v_cndmask_b32_e32 v108, v182, v108, vcc
	v_lshlrev_b32_e32 v173, 2, v108
	s_nop 0
	s_nop 0
	s_nop 0
	s_nop 0
	s_nop 0
	s_nop 0
	s_nop 0
	s_nop 0
	s_nop 0
	s_nop 0
	v_rcp_f32_e32 v3, v3
	s_nop 0
	s_nop 0
	s_nop 0
	s_nop 0
	s_nop 0
	s_nop 0
	v_lshlrev_b32_e32 v106, 16, v119
	v_and_b32_e32 v107, 0xffff0000, v119
	v_pk_fma_f32 v[106:107], v[88:89], v[106:107], 0 op_sel_hi:[1,1,0]
	s_nop 0
	v_pk_fma_f32 v[106:107], v[92:93], v[120:121], v[106:107]
	s_nop 0
	v_pk_fma_f32 v[106:107], v[96:97], v[122:123], v[106:107]
	v_rcp_f32_e32 v2, v2
	v_pk_fma_f32 v[106:107], v[100:101], v[124:125], v[106:107]
	v_pk_fma_f32 v[90:91], v[94:95], v[114:115], v[90:91]
	v_mul_f32_e32 v108, 0xbfb8aa3b, v106
	v_mul_f32_e32 v109, 0xbfb8aa3b, v107
	v_exp_f32_e32 v108, v108
	v_exp_f32_e32 v109, v109
	v_pk_fma_f32 v[90:91], v[98:99], v[116:117], v[90:91]
	v_lshlrev_b32_e32 v94, 16, v203
	v_and_b32_e32 v95, 0xffff0000, v203
	v_pk_add_f32 v[108:109], v[108:109], 1.0 op_sel_hi:[1,0]
	v_pk_fma_f32 v[94:95], v[102:103], v[94:95], v[90:91]
	s_nop 0
	s_nop 0
	s_nop 0
	s_nop 0
	s_nop 0
	s_nop 0
	s_nop 0
	s_nop 0
	s_nop 0
	s_nop 0
	s_nop 0
	s_nop 0
	v_rcp_f32_e32 v109, v109
	s_nop 0
	s_nop 0
	s_nop 0
	s_nop 0
	s_nop 0
	s_nop 0
	v_lshlrev_b32_e32 v110, 16, v118
	v_and_b32_e32 v111, 0xffff0000, v118
	v_lshlrev_b32_e32 v126, 16, v127
	v_and_b32_e32 v127, 0xffff0000, v127
	v_pk_fma_f32 v[110:111], v[74:75], v[110:111], 0 op_sel_hi:[1,1,0]
	v_lshlrev_b32_e32 v128, 16, v129
	v_and_b32_e32 v129, 0xffff0000, v129
	v_pk_fma_f32 v[110:111], v[78:79], v[126:127], v[110:111]
	s_nop 0
	s_waitcnt vmcnt(7)
	v_pk_fma_f32 v[110:111], v[86:87], v[128:129], v[110:111]
	s_nop 0
	v_pk_fma_f32 v[110:111], v[82:83], v[130:131], v[110:111]
	v_rcp_f32_e32 v108, v108
	v_mul_f32_e32 v118, 0xbfb8aa3b, v110
	v_mul_f32_e32 v119, 0xbfb8aa3b, v111
	v_exp_f32_e32 v118, v118
	v_exp_f32_e32 v119, v119
	v_mul_f32_e32 v90, 0xbfb8aa3b, v95
	v_exp_f32_e32 v91, v90
	v_mul_f32_e32 v90, 0xbfb8aa3b, v94
	v_pk_add_f32 v[118:119], v[118:119], 1.0 op_sel_hi:[1,0]
	v_exp_f32_e32 v90, v90
	s_nop 0
	s_nop 0
	s_nop 0
	s_nop 0
	s_nop 0
	s_nop 0
	s_nop 0
	s_nop 0
	s_nop 0
	s_nop 0
	s_nop 0
	s_nop 0
	v_rcp_f32_e32 v119, v119
	s_nop 0
	s_nop 0
	s_nop 0
	s_nop 0
	s_nop 0
	v_lshlrev_b32_e32 v164, 16, v165
	v_and_b32_e32 v165, 0xffff0000, v165
	s_nop 0
	v_lshlrev_b32_e32 v132, 16, v133
	v_and_b32_e32 v133, 0xffff0000, v133
	v_pk_fma_f32 v[164:165], v[72:73], v[164:165], 0 op_sel_hi:[1,1,0]
	v_lshlrev_b32_e32 v160, 16, v161
	v_and_b32_e32 v161, 0xffff0000, v161
	v_pk_fma_f32 v[164:165], v[76:77], v[132:133], v[164:165]
	v_lshlrev_b32_e32 v162, 16, v163
	v_and_b32_e32 v163, 0xffff0000, v163
	v_pk_fma_f32 v[164:165], v[84:85], v[160:161], v[164:165]
	s_nop 0
	v_pk_fma_f32 v[164:165], v[80:81], v[162:163], v[164:165]
	s_nop 0
	v_mul_f32_e32 v204, 0xbfb8aa3b, v164
	v_mul_f32_e32 v205, 0xbfb8aa3b, v165
	v_exp_f32_e32 v204, v204
	v_exp_f32_e32 v205, v205
	v_rcp_f32_e32 v118, v118
	v_pk_fma_f32 v[88:89], v[88:89], v[120:121], 0 op_sel_hi:[1,1,0]
	v_pk_fma_f32 v[74:75], v[74:75], v[126:127], 0 op_sel_hi:[1,1,0]
	v_pk_add_f32 v[204:205], v[204:205], 1.0 op_sel_hi:[1,0]
	v_pk_fma_f32 v[88:89], v[92:93], v[122:123], v[88:89]
	s_nop 0
	s_nop 0
	v_pk_fma_f32 v[88:89], v[96:97], v[124:125], v[88:89]
	v_lshlrev_b32_e32 v92, 16, v202
	v_and_b32_e32 v93, 0xffff0000, v202
	s_nop 0
	s_nop 0
	s_nop 0
	s_nop 0
	s_nop 0
	s_nop 0
	s_nop 0
	s_nop 0
	s_nop 0
	s_nop 0
	v_rcp_f32_e32 v205, v205
	v_pk_fma_f32 v[92:93], v[100:101], v[92:93], v[88:89]
	s_nop 0
	s_nop 0
	s_nop 0
	s_nop 0
	s_nop 0
	s_nop 0
	s_nop 0
	s_nop 0
	v_pk_add_f32 v[98:99], v[90:91], 1.0 op_sel_hi:[1,0]
	v_mul_f32_e32 v88, 0xbfb8aa3b, v92
	s_nop 0
	s_nop 0
	v_mul_f32_e32 v89, 0xbfb8aa3b, v93
	v_exp_f32_e32 v88, v88
	v_exp_f32_e32 v89, v89
	s_nop 0
	s_nop 0
	s_nop 0
	s_nop 0
	s_nop 0
	s_nop 0
	s_nop 0
	s_nop 0
	s_nop 0
	s_nop 0
	v_rcp_f32_e32 v99, v99
	v_pk_fma_f32 v[74:75], v[78:79], v[128:129], v[74:75]
	s_nop 0
	s_nop 0
	s_nop 0
	s_nop 0
	s_nop 0
	s_nop 0
	s_nop 0
	s_nop 0
	v_pk_add_f32 v[96:97], v[88:89], 1.0 op_sel_hi:[1,0]
	v_rcp_f32_e32 v98, v98
	s_nop 0
	s_nop 0
	v_pk_mul_f32 v[88:89], v[94:95], v[98:99]
	v_pk_fma_f32 v[74:75], v[86:87], v[130:131], v[74:75]
	v_lshlrev_b32_e32 v78, 16, v199
	s_nop 0
	s_nop 0
	s_nop 0
	s_nop 0
	s_nop 0
	s_nop 0
	s_nop 0
	s_nop 0
	s_nop 0
	v_and_b32_e32 v79, 0xffff0000, v199
	v_pk_fma_f32 v[74:75], v[82:83], v[78:79], v[74:75]
	s_nop 0
	v_mul_f32_e32 v78, 0xbfb8aa3b, v74
	v_mul_f32_e32 v79, 0xbfb8aa3b, v75
	v_rcp_f32_e32 v97, v97
	s_nop 0
	v_exp_f32_e32 v78, v78
	v_exp_f32_e32 v79, v79
	s_nop 0
	s_nop 0
	s_nop 0
	s_nop 0
	s_nop 0
	v_pk_add_f32 v[78:79], v[78:79], 1.0 op_sel_hi:[1,0]
	s_nop 0
	s_nop 0
	s_nop 0
	s_nop 0
	v_rcp_f32_e32 v96, v96
	s_nop 0
	v_pk_mul_f32 v[82:83], v[92:93], v[96:97]
	v_pk_fma_f32 v[72:73], v[72:73], v[132:133], 0 op_sel_hi:[1,1,0]
	s_nop 0
	s_nop 0
	s_nop 0
	s_nop 0
	s_nop 0
	v_pk_fma_f32 v[72:73], v[76:77], v[160:161], v[72:73]
	s_nop 0
	s_nop 0
	v_pk_fma_f32 v[72:73], v[84:85], v[162:163], v[72:73]
	v_lshlrev_b32_e32 v76, 16, v196
	v_and_b32_e32 v77, 0xffff0000, v196
	s_nop 0
	v_pk_fma_f32 v[72:73], v[80:81], v[76:77], v[72:73]
	s_nop 0
	v_mul_f32_e32 v76, 0xbfb8aa3b, v72
	v_mul_f32_e32 v77, 0xbfb8aa3b, v73
	v_exp_f32_e32 v76, v76
	v_exp_f32_e32 v77, v77
	s_nop 0
	v_rcp_f32_e32 v79, v79
	s_nop 0
	s_nop 0
	s_nop 0
	s_nop 0
	v_pk_add_f32 v[76:77], v[76:77], 1.0 op_sel_hi:[1,0]
	s_nop 0
	s_nop 0
	s_nop 0
	s_nop 0
	s_nop 0
	s_nop 0
	v_rcp_f32_e32 v78, v78
	s_nop 0
	v_pk_mul_f32 v[80:81], v[74:75], v[78:79]
	s_nop 0
	s_nop 0
	s_nop 0
	s_nop 0
	s_nop 0
	s_nop 0
	s_nop 0
	s_nop 0
	s_nop 0
	s_nop 0
	v_rcp_f32_e32 v77, v77
	v_rcp_f32_e32 v204, v204
	s_nop 0
	s_nop 0
	s_nop 0
	s_nop 0
	s_nop 0
	s_nop 0
	s_nop 0
	s_nop 0
	v_rcp_f32_e32 v76, v76
	v_pk_mul_f32 v[90:91], v[164:165], v[204:205]
	v_pk_mul_f32 v[84:85], v[72:73], v[76:77]
	v_pk_mul_f32 v[110:111], v[110:111], v[118:119]
	v_pk_mul_f32 v[102:103], v[90:91], v[90:91]
	v_pk_mul_f32 v[72:73], v[84:85], v[84:85]
	v_pk_mul_f32 v[118:119], v[110:111], v[110:111]
	v_pk_mul_f32 v[74:75], v[80:81], v[80:81]
	v_mov_b32_e32 v76, v72
	v_mov_b32_e32 v77, v102
	v_mov_b32_e32 v102, v73
	v_pk_mul_f32 v[106:107], v[106:107], v[108:109]
	v_pk_add_f32 v[72:73], v[76:77], v[102:103]
	v_mov_b32_e32 v76, v74
	v_mov_b32_e32 v77, v118
	v_pk_mul_f32 v[108:109], v[106:107], v[106:107]
	v_pk_mul_f32 v[86:87], v[82:83], v[82:83]
	v_pk_add_f32 v[72:73], v[76:77], v[72:73]
	v_mov_b32_e32 v118, v75
	v_pk_mul_f32 v[2:3], v[104:105], v[2:3]
	v_pk_add_f32 v[72:73], v[118:119], v[72:73]
	v_mov_b32_e32 v74, v86
	v_mov_b32_e32 v75, v108
	v_pk_mul_f32 v[104:105], v[2:3], v[2:3]
	v_pk_mul_f32 v[94:95], v[88:89], v[88:89]
	v_pk_add_f32 v[72:73], v[74:75], v[72:73]
	v_mov_b32_e32 v108, v87
	v_pk_add_f32 v[72:73], v[108:109], v[72:73]
	v_mov_b32_e32 v74, v94
	v_mov_b32_e32 v75, v104
	v_pk_add_f32 v[72:73], v[74:75], v[72:73]
	v_mov_b32_e32 v104, v95
	v_pk_add_f32 v[72:73], v[104:105], v[72:73]
	ds_bpermute_b32 v75, v173, v73
	ds_bpermute_b32 v74, v173, v72
	v_xor_b32_e32 v76, 2, v182
	v_cmp_lt_i32_e32 vcc, v76, v201
	s_mov_b32 s0, 0x27ffffc
	v_and_b32_e32 v77, 48, v197
	v_cndmask_b32_e32 v76, v182, v76, vcc
	v_lshlrev_b32_e32 v118, 2, v76
	s_waitcnt lgkmcnt(0)
	v_pk_add_f32 v[72:73], v[72:73], v[74:75]
	ds_bpermute_b32 v75, v118, v73
	ds_bpermute_b32 v74, v118, v72
	v_xor_b32_e32 v76, 4, v182
	v_cmp_lt_i32_e32 vcc, v76, v201
	v_add_u32_e32 v92, 0, v197
	s_add_i32 s25, 0, 0x20500
	v_cndmask_b32_e32 v76, v182, v76, vcc
	v_lshlrev_b32_e32 v119, 2, v76
	s_waitcnt lgkmcnt(0)
	v_pk_add_f32 v[72:73], v[72:73], v[74:75]
	ds_bpermute_b32 v75, v119, v73
	ds_bpermute_b32 v74, v119, v72
	v_xor_b32_e32 v76, 8, v182
	v_cmp_lt_i32_e32 vcc, v76, v201
	global_load_dwordx4 v[28:31], v[14:15], off
	s_nop 0
	global_load_dwordx4 v[12:15], v[12:13], off offset:16
	v_cndmask_b32_e32 v76, v182, v76, vcc
	v_lshlrev_b32_e32 v120, 2, v76
	s_waitcnt lgkmcnt(0)
	v_pk_add_f32 v[72:73], v[72:73], v[74:75]
	ds_bpermute_b32 v75, v120, v73
	ds_bpermute_b32 v74, v120, v72
	v_and_or_b32 v76, v198, s0, v200
	v_lshl_or_b32 v121, v76, 6, v77
	v_mad_u64_u32 v[76:77], s[0:1], v183, s54, v[92:93]
	s_waitcnt lgkmcnt(0)
	v_pk_add_f32 v[72:73], v[72:73], v[74:75]
	global_load_dwordx4 v[32:35], v[18:19], off
	s_nop 0
	global_load_dwordx4 v[16:19], v[16:17], off offset:16
	v_pk_add_f32 v[86:87], v[72:73], s[4:5] op_sel_hi:[1,0]
	global_load_dwordx4 v[36:39], v[20:21], off
	s_nop 0
	global_load_dwordx4 v[20:23], v[22:23], off offset:16
	v_mul_f32_e32 v72, 0x4b800000, v87
	v_cmp_gt_f32_e32 vcc, s51, v87
	v_lshl_add_u32 v77, v183, 2, s25
	s_add_u32 s0, s10, s16
	v_cndmask_b32_e32 v72, v87, v72, vcc
	v_rsq_f32_e32 v72, v72
	v_mul_f32_e32 v87, 0x4b800000, v86
	s_addc_u32 s1, s11, s17
	v_lshlrev_b32_e32 v100, 16, v194
	v_mul_f32_e32 v73, 0x45800000, v72
	v_cndmask_b32_e32 v72, v72, v73, vcc
	v_mul_f32_e32 v72, 0x3db504f3, v72
	v_pk_mul_f32 v[90:91], v[90:91], v[72:73] op_sel_hi:[1,0]
	v_pk_mul_f32 v[94:95], v[110:111], v[72:73] op_sel_hi:[1,0]
	v_pk_mul_f32 v[96:97], v[106:107], v[72:73] op_sel_hi:[1,0]
	v_pk_mul_f32 v[2:3], v[2:3], v[72:73] op_sel_hi:[1,0]
	v_cvt_pk_bf16_f32 v72, v90, v91
	v_cvt_pk_bf16_f32 v73, v94, v95
	v_cvt_pk_bf16_f32 v74, v96, v97
	v_cvt_pk_bf16_f32 v75, v2, v3
	ds_write_b128 v76, v[72:75] offset:17408
	ds_read_b32 v74, v77
	v_cmp_gt_f32_e32 vcc, s51, v86
	v_and_or_b32 v72, v181, 14, v121
	v_lshlrev_b32_e32 v72, 3, v72
	v_cndmask_b32_e32 v86, v86, v87, vcc
	s_waitcnt lgkmcnt(0)
	v_mul_f32_e32 v74, 0x3fb8aa3b, v74
	v_exp_f32_e32 v98, v74
	v_rsq_f32_e32 v86, v86
	v_ashrrev_i32_e32 v73, 31, v72
	v_lshl_add_u64 v[78:79], v[72:73], 1, s[0:1]
	v_pk_mul_f32 v[72:73], v[98:99], v[90:91] op_sel_hi:[0,1]
	v_pk_mul_f32 v[74:75], v[98:99], v[94:95] op_sel_hi:[0,1]
	v_cvt_pk_bf16_f32 v72, v72, v73
	v_cvt_pk_bf16_f32 v73, v74, v75
	v_pk_mul_f32 v[74:75], v[98:99], v[96:97] op_sel_hi:[0,1]
	v_pk_mul_f32 v[2:3], v[98:99], v[2:3] op_sel_hi:[0,1]
	v_cvt_pk_bf16_f32 v74, v74, v75
	v_cvt_pk_bf16_f32 v75, v2, v3
	v_mul_f32_e32 v2, 0x45800000, v86
	v_cndmask_b32_e32 v2, v86, v2, vcc
	v_mul_f32_e32 v2, 0x3db504f3, v2
	v_pk_mul_f32 v[86:87], v[84:85], v[2:3] op_sel_hi:[1,0]
	v_pk_mul_f32 v[84:85], v[80:81], v[2:3] op_sel_hi:[1,0]
	v_pk_mul_f32 v[82:83], v[82:83], v[2:3] op_sel_hi:[1,0]
	v_pk_mul_f32 v[80:81], v[88:89], v[2:3] op_sel_hi:[1,0]
	v_lshlrev_b32_e32 v2, 16, v192
	v_and_b32_e32 v3, 0xffff0000, v192
	v_lshlrev_b32_e32 v98, 16, v193
	v_and_b32_e32 v99, 0xffff0000, v193
	v_pk_fma_f32 v[2:3], v[58:59], v[2:3], 0 op_sel_hi:[1,1,0]
	v_and_b32_e32 v101, 0xffff0000, v194
	s_waitcnt vmcnt(11)
	v_pk_fma_f32 v[2:3], v[66:67], v[98:99], v[2:3]
	v_lshlrev_b32_e32 v102, 16, v195
	v_and_b32_e32 v103, 0xffff0000, v195
	s_waitcnt vmcnt(10)
	v_pk_fma_f32 v[2:3], v[70:71], v[100:101], v[2:3]
	v_or_b32_e32 v77, 1, v181
	s_waitcnt vmcnt(8)
	v_pk_fma_f32 v[94:95], v[62:63], v[102:103], v[2:3]
	v_cvt_pk_bf16_f32 v88, v86, v87
	v_mul_f32_e32 v2, 0xbfb8aa3b, v95
	v_exp_f32_e32 v97, v2
	v_mul_f32_e32 v2, 0xbfb8aa3b, v94
	v_exp_f32_e32 v96, v2
	v_mad_u64_u32 v[2:3], s[2:3], v77, s54, v[92:93]
	v_cvt_pk_bf16_f32 v89, v84, v85
	v_pk_add_f32 v[92:93], v[96:97], 1.0 op_sel_hi:[1,0]
	v_cvt_pk_bf16_f32 v90, v82, v83
	s_nop 0
	s_nop 0
	v_cvt_pk_bf16_f32 v91, v80, v81
	ds_write_b128 v2, v[88:91] offset:17408
	s_nop 0
	s_nop 0
	s_nop 0
	s_nop 0
	s_nop 0
	s_nop 0
	s_nop 0
	s_nop 0
	s_nop 0
	s_nop 0
	v_rcp_f32_e32 v89, v93
	s_nop 0
	s_nop 0
	s_nop 0
	s_nop 0
	s_nop 0
	s_nop 0
	v_lshlrev_b32_e32 v90, 16, v188
	v_and_b32_e32 v91, 0xffff0000, v188
	v_lshlrev_b32_e32 v106, 16, v189
	v_and_b32_e32 v107, 0xffff0000, v189
	v_pk_fma_f32 v[90:91], v[56:57], v[90:91], 0 op_sel_hi:[1,1,0]
	v_lshlrev_b32_e32 v108, 16, v190
	v_and_b32_e32 v109, 0xffff0000, v190
	v_pk_fma_f32 v[90:91], v[64:65], v[106:107], v[90:91]
	v_lshlrev_b32_e32 v110, 16, v191
	v_and_b32_e32 v111, 0xffff0000, v191
	v_pk_fma_f32 v[90:91], v[68:69], v[108:109], v[90:91]
	s_nop 0
	v_pk_fma_f32 v[96:97], v[60:61], v[110:111], v[90:91]
	s_nop 0
	v_mul_f32_e32 v90, 0xbfb8aa3b, v96
	v_mul_f32_e32 v91, 0xbfb8aa3b, v97
	v_exp_f32_e32 v90, v90
	v_exp_f32_e32 v91, v91
	v_rcp_f32_e32 v88, v92
	s_nop 0
	v_pk_mul_f32 v[88:89], v[94:95], v[88:89]
	v_and_b32_e32 v113, 0xffff0000, v185
	v_pk_add_f32 v[104:105], v[90:91], 1.0 op_sel_hi:[1,0]
	v_lshlrev_b32_e32 v114, 16, v186
	s_nop 0
	s_nop 0
	s_nop 0
	s_nop 0
	s_nop 0
	s_nop 0
	s_nop 0
	s_nop 0
	s_nop 0
	s_nop 0
	s_nop 0
	s_nop 0
	v_rcp_f32_e32 v93, v105
	s_nop 0
	s_nop 0
	s_nop 0
	s_nop 0
	s_nop 0
	s_nop 0
	v_lshlrev_b32_e32 v94, 16, v184
	v_and_b32_e32 v95, 0xffff0000, v184
	v_lshlrev_b32_e32 v112, 16, v185
	v_pk_fma_f32 v[94:95], v[42:43], v[94:95], 0 op_sel_hi:[1,1,0]
	v_and_b32_e32 v115, 0xffff0000, v186
	v_pk_fma_f32 v[94:95], v[46:47], v[112:113], v[94:95]
	v_lshlrev_b32_e32 v116, 16, v187
	v_and_b32_e32 v117, 0xffff0000, v187
	v_pk_fma_f32 v[94:95], v[50:51], v[114:115], v[94:95]
	s_nop 0
	v_pk_fma_f32 v[122:123], v[54:55], v[116:117], v[94:95]
	s_nop 0
	v_mul_f32_e32 v94, 0xbfb8aa3b, v122
	v_mul_f32_e32 v95, 0xbfb8aa3b, v123
	v_exp_f32_e32 v94, v94
	v_exp_f32_e32 v95, v95
	v_rcp_f32_e32 v92, v104
	s_nop 0
	v_pk_mul_f32 v[92:93], v[96:97], v[92:93]
	v_and_b32_e32 v127, 0xffff0000, v178
	v_pk_add_f32 v[124:125], v[94:95], 1.0 op_sel_hi:[1,0]
	v_lshlrev_b32_e32 v128, 16, v179
	s_nop 0
	s_nop 0
	s_nop 0
	s_nop 0
	s_nop 0
	s_nop 0
	s_nop 0
	s_nop 0
	s_nop 0
	s_nop 0
	s_nop 0
	s_nop 0
	v_rcp_f32_e32 v97, v125
	s_nop 0
	s_nop 0
	s_nop 0
	s_nop 0
	s_nop 0
	s_nop 0
	v_lshlrev_b32_e32 v104, 16, v177
	v_and_b32_e32 v105, 0xffff0000, v177
	v_lshlrev_b32_e32 v126, 16, v178
	v_pk_fma_f32 v[104:105], v[40:41], v[104:105], 0 op_sel_hi:[1,1,0]
	v_and_b32_e32 v129, 0xffff0000, v179
	v_pk_fma_f32 v[104:105], v[44:45], v[126:127], v[104:105]
	v_lshlrev_b32_e32 v130, 16, v180
	v_and_b32_e32 v131, 0xffff0000, v180
	v_pk_fma_f32 v[104:105], v[48:49], v[128:129], v[104:105]
	s_nop 0
	v_pk_fma_f32 v[132:133], v[52:53], v[130:131], v[104:105]
	s_nop 0
	v_mul_f32_e32 v104, 0xbfb8aa3b, v132
	v_mul_f32_e32 v105, 0xbfb8aa3b, v133
	v_exp_f32_e32 v104, v104
	v_exp_f32_e32 v105, v105
	v_rcp_f32_e32 v96, v124
	s_nop 0
	v_pk_mul_f32 v[96:97], v[122:123], v[96:97]
	v_pk_fma_f32 v[58:59], v[58:59], v[98:99], 0 op_sel_hi:[1,1,0]
	v_pk_add_f32 v[160:161], v[104:105], 1.0 op_sel_hi:[1,0]
	v_pk_fma_f32 v[58:59], v[66:67], v[100:101], v[58:59]
	s_nop 0
	s_nop 0
	v_pk_fma_f32 v[58:59], v[70:71], v[102:103], v[58:59]
	v_lshlrev_b32_e32 v66, 16, v176
	v_and_b32_e32 v67, 0xffff0000, v176
	s_nop 0
	s_nop 0
	s_nop 0
	s_nop 0
	s_nop 0
	s_nop 0
	s_nop 0
	s_nop 0
	s_nop 0
	s_nop 0
	v_pk_fma_f32 v[62:63], v[62:63], v[66:67], v[58:59]
	v_rcp_f32_e32 v123, v161
	s_nop 0
	v_mul_f32_e32 v58, 0xbfb8aa3b, v63
	s_nop 0
	s_nop 0
	v_exp_f32_e32 v59, v58
	v_mul_f32_e32 v58, 0xbfb8aa3b, v62
	s_nop 0
	v_exp_f32_e32 v58, v58
	s_nop 0
	s_nop 0
	s_nop 0
	s_nop 0
	v_pk_add_f32 v[66:67], v[58:59], 1.0 op_sel_hi:[1,0]
	v_pk_fma_f32 v[56:57], v[56:57], v[106:107], 0 op_sel_hi:[1,1,0]
	s_nop 0
	s_nop 0
	v_pk_fma_f32 v[56:57], v[64:65], v[108:109], v[56:57]
	v_lshlrev_b32_e32 v64, 16, v175
	v_pk_fma_f32 v[56:57], v[68:69], v[110:111], v[56:57]
	s_nop 0
	s_nop 0
	s_nop 0
	s_nop 0
	s_nop 0
	s_nop 0
	s_nop 0
	s_nop 0
	s_nop 0
	s_nop 0
	v_and_b32_e32 v65, 0xffff0000, v175
	v_rcp_f32_e32 v67, v67
	s_nop 0
	v_pk_fma_f32 v[60:61], v[60:61], v[64:65], v[56:57]
	s_nop 0
	s_nop 0
	v_mul_f32_e32 v56, 0xbfb8aa3b, v60
	v_mul_f32_e32 v57, 0xbfb8aa3b, v61
	s_nop 0
	v_exp_f32_e32 v56, v56
	v_exp_f32_e32 v57, v57
	s_nop 0
	s_nop 0
	s_nop 0
	s_nop 0
	v_pk_add_f32 v[64:65], v[56:57], 1.0 op_sel_hi:[1,0]
	v_rcp_f32_e32 v66, v66
	s_nop 0
	s_nop 0
	v_pk_mul_f32 v[56:57], v[62:63], v[66:67]
	v_pk_fma_f32 v[42:43], v[42:43], v[112:113], 0 op_sel_hi:[1,1,0]
	v_pk_fma_f32 v[40:41], v[40:41], v[126:127], 0 op_sel_hi:[1,1,0]
	s_nop 0
	s_nop 0
	s_nop 0
	s_nop 0
	s_nop 0
	s_nop 0
	s_nop 0
	s_nop 0
	s_nop 0
	v_pk_fma_f32 v[42:43], v[46:47], v[114:115], v[42:43]
	v_lshlrev_b32_e32 v46, 16, v174
	v_pk_fma_f32 v[42:43], v[50:51], v[116:117], v[42:43]
	v_and_b32_e32 v47, 0xffff0000, v174
	v_pk_fma_f32 v[42:43], v[54:55], v[46:47], v[42:43]
	s_nop 0
	v_mul_f32_e32 v46, 0xbfb8aa3b, v42
	v_mul_f32_e32 v47, 0xbfb8aa3b, v43
	v_rcp_f32_e32 v65, v65
	s_nop 0
	v_exp_f32_e32 v46, v46
	v_exp_f32_e32 v47, v47
	s_nop 0
	s_nop 0
	s_nop 0
	s_nop 0
	s_nop 0
	v_pk_add_f32 v[46:47], v[46:47], 1.0 op_sel_hi:[1,0]
	s_nop 0
	s_nop 0
	s_nop 0
	s_nop 0
	v_rcp_f32_e32 v64, v64
	s_nop 0
	v_pk_mul_f32 v[50:51], v[60:61], v[64:65]
	v_pk_fma_f32 v[40:41], v[44:45], v[128:129], v[40:41]
	s_nop 0
	s_nop 0
	s_nop 0
	s_nop 0
	s_nop 0
	v_pk_fma_f32 v[40:41], v[48:49], v[130:131], v[40:41]
	v_lshlrev_b32_e32 v44, 16, v172
	v_and_b32_e32 v45, 0xffff0000, v172
	s_nop 0
	s_nop 0
	v_pk_fma_f32 v[40:41], v[52:53], v[44:45], v[40:41]
	s_nop 0
	v_mul_f32_e32 v44, 0xbfb8aa3b, v40
	v_mul_f32_e32 v45, 0xbfb8aa3b, v41
	v_exp_f32_e32 v44, v44
	v_exp_f32_e32 v45, v45
	s_nop 0
	s_nop 0
	v_rcp_f32_e32 v47, v47
	s_nop 0
	s_nop 0
	s_nop 0
	v_pk_add_f32 v[44:45], v[44:45], 1.0 op_sel_hi:[1,0]
	s_nop 0
	s_nop 0
	s_nop 0
	s_nop 0
	s_nop 0
	s_nop 0
	s_nop 0
	v_rcp_f32_e32 v46, v46
	s_nop 0
	s_nop 0
	s_nop 0
	s_nop 0
	s_nop 0
	s_nop 0
	s_nop 0
	s_nop 0
	s_nop 0
	s_nop 0
	v_rcp_f32_e32 v45, v45
	v_rcp_f32_e32 v122, v160
	s_nop 0
	s_nop 0
	s_nop 0
	s_nop 0
	s_nop 0
	s_nop 0
	s_nop 0
	s_nop 0
	v_rcp_f32_e32 v44, v44
	v_pk_mul_f32 v[58:59], v[132:133], v[122:123]
	v_pk_mul_f32 v[44:45], v[40:41], v[44:45]
	v_pk_mul_f32 v[70:71], v[58:59], v[58:59]
	v_pk_mul_f32 v[46:47], v[42:43], v[46:47]
	v_pk_mul_f32 v[40:41], v[44:45], v[44:45]
	v_pk_mul_f32 v[104:105], v[96:97], v[96:97]
	v_pk_mul_f32 v[42:43], v[46:47], v[46:47]
	v_mov_b32_e32 v48, v40
	v_mov_b32_e32 v49, v70
	v_mov_b32_e32 v70, v41
	v_pk_add_f32 v[40:41], v[48:49], v[70:71]
	v_mov_b32_e32 v48, v42
	v_mov_b32_e32 v49, v104
	v_pk_mul_f32 v[94:95], v[92:93], v[92:93]
	v_pk_mul_f32 v[54:55], v[50:51], v[50:51]
	v_pk_add_f32 v[40:41], v[48:49], v[40:41]
	v_mov_b32_e32 v104, v43
	v_pk_add_f32 v[40:41], v[104:105], v[40:41]
	v_mov_b32_e32 v42, v54
	v_mov_b32_e32 v43, v94
	v_pk_mul_f32 v[90:91], v[88:89], v[88:89]
	v_pk_mul_f32 v[62:63], v[56:57], v[56:57]
	v_pk_add_f32 v[40:41], v[42:43], v[40:41]
	v_mov_b32_e32 v94, v55
	v_pk_add_f32 v[40:41], v[94:95], v[40:41]
	v_mov_b32_e32 v42, v62
	v_mov_b32_e32 v43, v90
	v_pk_add_f32 v[40:41], v[42:43], v[40:41]
	v_mov_b32_e32 v90, v63
	v_pk_add_f32 v[40:41], v[90:91], v[40:41]
	v_lshl_add_u32 v3, v77, 2, s25
	ds_bpermute_b32 v43, v173, v41
	ds_bpermute_b32 v42, v173, v40
	ds_read_b32 v3, v3
	s_mov_b32 s2, 0x13800000
	v_add_co_u32_e32 v48, vcc, s2, v78
	s_waitcnt lgkmcnt(1)
	v_pk_add_f32 v[42:43], v[40:41], v[42:43]
	v_addc_co_u32_e32 v49, vcc, 0, v79, vcc
	s_waitcnt lgkmcnt(0)
	v_mul_f32_e32 v3, 0x3fb8aa3b, v3
	ds_bpermute_b32 v53, v118, v43
	ds_bpermute_b32 v52, v118, v42
	global_store_dwordx4 v[48:49], v[72:75], off nt
	v_exp_f32_e32 v48, v3
	v_and_or_b32 v3, v77, 15, v121
	v_lshlrev_b32_e32 v66, 16, v144
	s_waitcnt lgkmcnt(0)
	v_pk_add_f32 v[52:53], v[42:43], v[52:53]
	v_pk_mul_f32 v[40:41], v[48:49], v[86:87] op_sel_hi:[0,1]
	v_pk_mul_f32 v[54:55], v[48:49], v[84:85] op_sel_hi:[0,1]
	v_cvt_pk_bf16_f32 v40, v40, v41
	v_cvt_pk_bf16_f32 v41, v54, v55
	ds_bpermute_b32 v55, v119, v53
	ds_bpermute_b32 v54, v119, v52
	v_pk_mul_f32 v[42:43], v[48:49], v[82:83] op_sel_hi:[0,1]
	v_pk_mul_f32 v[48:49], v[48:49], v[80:81] op_sel_hi:[0,1]
	v_cvt_pk_bf16_f32 v42, v42, v43
	v_cvt_pk_bf16_f32 v43, v48, v49
	s_waitcnt lgkmcnt(0)
	v_pk_add_f32 v[48:49], v[52:53], v[54:55]
	ds_bpermute_b32 v53, v120, v49
	ds_bpermute_b32 v52, v120, v48
	v_lshlrev_b32_e32 v54, 3, v3
	v_ashrrev_i32_e32 v55, 31, v54
	v_lshl_add_u64 v[54:55], v[54:55], 1, s[0:1]
	v_and_b32_e32 v67, 0xffff0000, v144
	s_waitcnt lgkmcnt(0)
	v_pk_add_f32 v[48:49], v[48:49], v[52:53]
	v_add_co_u32_e64 v52, s[0:1], s2, v54
	v_pk_add_f32 v[48:49], v[48:49], s[4:5] op_sel_hi:[1,0]
	s_nop 0
	v_addc_co_u32_e64 v53, s[0:1], 0, v55, s[0:1]
	v_mul_f32_e32 v3, 0x4b800000, v49
	v_cmp_gt_f32_e32 vcc, s51, v49
	global_store_dwordx4 v[52:53], v[40:43], off nt
	s_waitcnt vmcnt(9)
	v_pk_fma_f32 v[66:67], v[8:9], v[66:67], 0 op_sel_hi:[1,1,0]
	v_cndmask_b32_e32 v3, v49, v3, vcc
	v_rsq_f32_e32 v3, v3
	v_and_b32_e32 v73, 0xffff0000, v140
	s_bfe_u32 s28, s24, 0x20006
	s_ashr_i32 s26, s24, 7
	v_mul_f32_e32 v40, 0x45800000, v3
	v_cndmask_b32_e32 v40, v3, v40, vcc
	v_mul_f32_e32 v3, 0x4b800000, v48
	v_cmp_gt_f32_e32 vcc, s51, v48
	v_pk_mul_f32 v[42:43], v[58:59], v[40:41] op_sel_hi:[1,0]
	v_pk_mul_f32 v[52:53], v[96:97], v[40:41] op_sel_hi:[1,0]
	v_cndmask_b32_e32 v3, v48, v3, vcc
	v_rsq_f32_e32 v3, v3
	v_pk_mul_f32 v[54:55], v[92:93], v[40:41] op_sel_hi:[1,0]
	v_pk_mul_f32 v[58:59], v[88:89], v[40:41] op_sel_hi:[1,0]
	v_cvt_pk_bf16_f32 v40, v42, v43
	v_cvt_pk_bf16_f32 v41, v52, v53
	v_cvt_pk_bf16_f32 v42, v54, v55
	v_cvt_pk_bf16_f32 v43, v58, v59
	ds_write_b128 v76, v[40:43]
	v_mul_f32_e32 v40, 0x45800000, v3
	v_cndmask_b32_e32 v48, v3, v40, vcc
	v_pk_mul_f32 v[54:55], v[46:47], v[48:49] op_sel_hi:[1,0]
	v_lshlrev_b32_e32 v46, 16, v168
	v_and_b32_e32 v47, 0xffff0000, v168
	v_lshlrev_b32_e32 v40, 16, v169
	v_and_b32_e32 v41, 0xffff0000, v169
	s_waitcnt vmcnt(8)
	v_pk_fma_f32 v[46:47], v[24:25], v[46:47], 0 op_sel_hi:[1,1,0]
	v_lshlrev_b32_e32 v42, 16, v170
	v_and_b32_e32 v43, 0xffff0000, v170
	s_waitcnt vmcnt(7)
	v_pk_fma_f32 v[46:47], v[28:29], v[40:41], v[46:47]
	v_pk_mul_f32 v[52:53], v[44:45], v[48:49] op_sel_hi:[1,0]
	v_lshlrev_b32_e32 v44, 16, v171
	v_and_b32_e32 v45, 0xffff0000, v171
	s_waitcnt vmcnt(5)
	v_pk_fma_f32 v[46:47], v[32:33], v[42:43], v[46:47]
	v_pk_mul_f32 v[50:51], v[50:51], v[48:49] op_sel_hi:[1,0]
	s_waitcnt vmcnt(3)
	v_pk_fma_f32 v[58:59], v[36:37], v[44:45], v[46:47]
	v_cvt_pk_bf16_f32 v46, v52, v53
	v_mul_f32_e32 v3, 0xbfb8aa3b, v58
	v_exp_f32_e32 v60, v3
	v_mul_f32_e32 v3, 0xbfb8aa3b, v59
	v_exp_f32_e32 v61, v3
	v_cvt_pk_bf16_f32 v47, v54, v55
	v_pk_mul_f32 v[56:57], v[56:57], v[48:49] op_sel_hi:[1,0]
	v_cvt_pk_bf16_f32 v48, v50, v51
	v_pk_add_f32 v[52:53], v[60:61], 1.0 op_sel_hi:[1,0]
	v_cvt_pk_bf16_f32 v49, v56, v57
	s_nop 0
	s_nop 0
	ds_write_b128 v2, v[46:49]
	v_and_b32_e32 v55, 0xffff0000, v148
	s_nop 0
	s_nop 0
	s_nop 0
	s_nop 0
	s_nop 0
	s_nop 0
	s_nop 0
	s_nop 0
	s_nop 0
	v_lshlrev_b32_e32 v54, 16, v148
	v_lshlrev_b32_e32 v46, 16, v149
	v_and_b32_e32 v47, 0xffff0000, v149
	v_pk_fma_f32 v[54:55], v[26:27], v[54:55], 0 op_sel_hi:[1,1,0]
	s_nop 0
	v_lshlrev_b32_e32 v48, 16, v150
	v_and_b32_e32 v49, 0xffff0000, v150
	v_pk_fma_f32 v[54:55], v[30:31], v[46:47], v[54:55]
	v_lshlrev_b32_e32 v50, 16, v151
	v_and_b32_e32 v51, 0xffff0000, v151
	v_pk_fma_f32 v[54:55], v[34:35], v[48:49], v[54:55]
	v_rcp_f32_e32 v53, v53
	v_pk_fma_f32 v[60:61], v[38:39], v[50:51], v[54:55]
	s_nop 0
	v_mul_f32_e32 v54, 0xbfb8aa3b, v60
	v_mul_f32_e32 v55, 0xbfb8aa3b, v61
	v_exp_f32_e32 v54, v54
	v_exp_f32_e32 v55, v55
	s_nop 0
	s_nop 0
	s_nop 0
	s_nop 0
	s_nop 0
	v_pk_add_f32 v[62:63], v[54:55], 1.0 op_sel_hi:[1,0]
	s_nop 0
	s_nop 0
	s_nop 0
	s_nop 0
	v_rcp_f32_e32 v52, v52
	s_nop 0
	v_pk_mul_f32 v[64:65], v[58:59], v[52:53]
	s_nop 0
	s_nop 0
	s_nop 0
	s_nop 0
	s_nop 0
	s_nop 0
	s_nop 0
	s_nop 0
	v_lshlrev_b32_e32 v52, 16, v145
	v_and_b32_e32 v53, 0xffff0000, v145
	s_nop 0
	v_lshlrev_b32_e32 v54, 16, v146
	v_and_b32_e32 v55, 0xffff0000, v146
	v_pk_fma_f32 v[66:67], v[12:13], v[52:53], v[66:67]
	s_nop 0
	v_lshlrev_b32_e32 v56, 16, v147
	v_and_b32_e32 v57, 0xffff0000, v147
	v_pk_fma_f32 v[66:67], v[16:17], v[54:55], v[66:67]
	v_rcp_f32_e32 v59, v63
	s_waitcnt vmcnt(2)
	v_pk_fma_f32 v[66:67], v[20:21], v[56:57], v[66:67]
	s_nop 0
	v_mul_f32_e32 v68, 0xbfb8aa3b, v66
	v_mul_f32_e32 v69, 0xbfb8aa3b, v67
	v_exp_f32_e32 v68, v68
	v_exp_f32_e32 v69, v69
	s_nop 0
	s_nop 0
	s_nop 0
	s_nop 0
	v_pk_add_f32 v[68:69], v[68:69], 1.0 op_sel_hi:[1,0]
	s_nop 0
	s_nop 0
	s_nop 0
	s_nop 0
	s_nop 0
	v_rcp_f32_e32 v58, v62
	s_nop 0
	s_nop 0
	s_nop 0
	v_pk_mul_f32 v[62:63], v[60:61], v[58:59]
	s_nop 0
	s_nop 0
	s_nop 0
	s_nop 0
	s_nop 0
	v_lshlrev_b32_e32 v72, 16, v140
	v_lshlrev_b32_e32 v58, 16, v141
	v_and_b32_e32 v59, 0xffff0000, v141
	v_pk_fma_f32 v[72:73], v[10:11], v[72:73], 0 op_sel_hi:[1,1,0]
	s_nop 0
	v_lshlrev_b32_e32 v60, 16, v142
	v_and_b32_e32 v61, 0xffff0000, v142
	v_pk_fma_f32 v[72:73], v[14:15], v[58:59], v[72:73]
	s_nop 0
	v_lshlrev_b32_e32 v70, 16, v143
	v_and_b32_e32 v71, 0xffff0000, v143
	v_pk_fma_f32 v[72:73], v[18:19], v[60:61], v[72:73]
	v_rcp_f32_e32 v69, v69
	v_pk_fma_f32 v[72:73], v[22:23], v[70:71], v[72:73]
	s_nop 0
	v_mul_f32_e32 v74, 0xbfb8aa3b, v73
	v_exp_f32_e32 v75, v74
	v_mul_f32_e32 v74, 0xbfb8aa3b, v72
	v_exp_f32_e32 v74, v74
	s_nop 0
	s_nop 0
	s_nop 0
	s_nop 0
	s_nop 0
	v_pk_add_f32 v[74:75], v[74:75], 1.0 op_sel_hi:[1,0]
	s_nop 0
	s_nop 0
	s_nop 0
	s_nop 0
	v_rcp_f32_e32 v68, v68
	s_nop 0
	v_pk_mul_f32 v[66:67], v[66:67], v[68:69]
	s_nop 0
	s_nop 0
	s_nop 0
	s_nop 0
	s_nop 0
	s_nop 0
	s_nop 0
	s_nop 0
	s_nop 0
	s_nop 0
	v_rcp_f32_e32 v69, v75
	v_pk_fma_f32 v[24:25], v[24:25], v[40:41], 0 op_sel_hi:[1,1,0]
	s_nop 0
	s_nop 0
	s_nop 0
	s_nop 0
	s_nop 0
	s_nop 0
	v_pk_fma_f32 v[24:25], v[28:29], v[42:43], v[24:25]
	s_nop 0
	v_pk_fma_f32 v[24:25], v[32:33], v[44:45], v[24:25]
	v_lshlrev_b32_e32 v28, 16, v139
	v_and_b32_e32 v29, 0xffff0000, v139
	s_nop 0
	v_pk_fma_f32 v[24:25], v[36:37], v[28:29], v[24:25]
	v_rcp_f32_e32 v68, v74
	v_mul_f32_e32 v3, 0xbfb8aa3b, v24
	v_exp_f32_e32 v28, v3
	v_mul_f32_e32 v3, 0xbfb8aa3b, v25
	v_exp_f32_e32 v29, v3
	v_pk_mul_f32 v[32:33], v[72:73], v[68:69]
	v_pk_fma_f32 v[26:27], v[26:27], v[46:47], 0 op_sel_hi:[1,1,0]
	v_cvt_pk_bf16_f32 v43, v32, v33
	v_pk_add_f32 v[28:29], v[28:29], 1.0 op_sel_hi:[1,0]
	v_pk_fma_f32 v[26:27], v[30:31], v[48:49], v[26:27]
	s_nop 0
	s_nop 0
	v_pk_fma_f32 v[26:27], v[34:35], v[50:51], v[26:27]
	v_lshlrev_b32_e32 v30, 16, v138
	v_and_b32_e32 v31, 0xffff0000, v138
	s_nop 0
	s_nop 0
	s_nop 0
	s_nop 0
	s_nop 0
	s_nop 0
	s_nop 0
	s_nop 0
	s_nop 0
	v_pk_fma_f32 v[26:27], v[38:39], v[30:31], v[26:27]
	s_nop 0
	v_mul_f32_e32 v30, 0xbfb8aa3b, v26
	v_mul_f32_e32 v31, 0xbfb8aa3b, v27
	v_rcp_f32_e32 v29, v29
	s_nop 0
	v_exp_f32_e32 v30, v30
	v_exp_f32_e32 v31, v31
	s_nop 0
	s_nop 0
	s_nop 0
	s_nop 0
	s_nop 0
	v_pk_add_f32 v[30:31], v[30:31], 1.0 op_sel_hi:[1,0]
	s_nop 0
	s_nop 0
	s_nop 0
	s_nop 0
	v_rcp_f32_e32 v28, v28
	s_nop 0
	v_pk_mul_f32 v[24:25], v[24:25], v[28:29]
	s_nop 0
	s_nop 0
	s_nop 0
	s_nop 0
	v_pk_fma_f32 v[8:9], v[8:9], v[52:53], 0 op_sel_hi:[1,1,0]
	s_nop 0
	v_pk_fma_f32 v[8:9], v[12:13], v[54:55], v[8:9]
	s_nop 0
	v_pk_fma_f32 v[8:9], v[16:17], v[56:57], v[8:9]
	v_lshlrev_b32_e32 v12, 16, v137
	v_and_b32_e32 v13, 0xffff0000, v137
	s_nop 0
	s_nop 0
	v_pk_fma_f32 v[8:9], v[20:21], v[12:13], v[8:9]
	s_nop 0
	v_mul_f32_e32 v12, 0xbfb8aa3b, v8
	v_mul_f32_e32 v13, 0xbfb8aa3b, v9
	v_exp_f32_e32 v12, v12
	v_exp_f32_e32 v13, v13
	s_nop 0
	v_rcp_f32_e32 v29, v31
	s_nop 0
	s_nop 0
	s_nop 0
	v_pk_add_f32 v[12:13], v[12:13], 1.0 op_sel_hi:[1,0]
	s_nop 0
	s_nop 0
	s_nop 0
	s_nop 0
	s_nop 0
	s_nop 0
	s_nop 0
	v_rcp_f32_e32 v28, v30
	s_nop 0
	s_nop 0
	s_nop 0
	v_pk_mul_f32 v[16:17], v[26:27], v[28:29]
	s_nop 0
	s_nop 0
	v_pk_fma_f32 v[10:11], v[10:11], v[58:59], 0 op_sel_hi:[1,1,0]
	s_nop 0
	v_pk_fma_f32 v[10:11], v[14:15], v[60:61], v[10:11]
	s_nop 0
	s_nop 0
	v_pk_fma_f32 v[10:11], v[18:19], v[70:71], v[10:11]
	v_lshlrev_b32_e32 v14, 16, v136
	v_and_b32_e32 v15, 0xffff0000, v136
	s_nop 0
	v_pk_fma_f32 v[10:11], v[22:23], v[14:15], v[10:11]
	s_nop 0
	v_mul_f32_e32 v14, 0xbfb8aa3b, v11
	v_exp_f32_e32 v15, v14
	v_mul_f32_e32 v14, 0xbfb8aa3b, v10
	v_exp_f32_e32 v14, v14
	v_rcp_f32_e32 v13, v13
	s_nop 0
	s_nop 0
	s_nop 0
	s_nop 0
	s_nop 0
	v_pk_add_f32 v[14:15], v[14:15], 1.0 op_sel_hi:[1,0]
	s_nop 0
	s_nop 0
	s_nop 0
	s_nop 0
	s_nop 0
	v_rcp_f32_e32 v12, v12
	s_nop 0
	s_nop 0
	s_nop 0
	v_pk_mul_f32 v[12:13], v[8:9], v[12:13]
	s_nop 0
	s_nop 0
	s_nop 0
	s_nop 0
	s_nop 0
	s_nop 0
	s_nop 0
	v_rcp_f32_e32 v9, v15
	s_lshl_b32 s29, s28, 4
	s_nop 0
	s_nop 0
	s_nop 0
	s_nop 0
	s_nop 0
	s_nop 0
	s_nop 0
	s_nop 0
	v_rcp_f32_e32 v8, v14
	s_nop 0
	v_pk_mul_f32 v[14:15], v[10:11], v[8:9]
	v_cvt_pk_bf16_f32 v8, v24, v25
	v_cvt_pk_bf16_f32 v9, v16, v17
	v_cvt_pk_bf16_f32 v10, v12, v13
	v_cvt_pk_bf16_f32 v11, v14, v15
	v_and_b32_e32 v3, 48, v134
	ds_write_b128 v2, v[8:11] offset:34816
	s_and_b32 s27, s26, -2
	v_or_b32_e32 v2, s29, v1
	v_add_u32_e32 v48, 0, v3
	v_cvt_pk_bf16_f32 v40, v64, v65
	v_cvt_pk_bf16_f32 v41, v62, v63
	v_cvt_pk_bf16_f32 v42, v66, v67
	v_mad_u32_u24 v55, v2, s54, v48
	v_lshl_or_b32 v59, s27, 4, v1
	ds_write_b128 v76, v[40:43] offset:34816
	s_waitcnt lgkmcnt(0)
	s_barrier
	v_mad_u64_u32 v[2:3], s[0:1], v59, s54, v[48:49]
	ds_read_b128 v[28:31], v55
	ds_read_b128 v[20:23], v55 offset:64
	ds_read_b128 v[40:43], v2
	ds_read_b128 v[44:47], v2 offset:64
	ds_read_b128 v[36:39], v2 offset:17408
	ds_read_b128 v[32:35], v2 offset:17472
	ds_read_b128 v[12:15], v55 offset:128
	ds_read_b128 v[8:11], v55 offset:192
	ds_read_b128 v[62:65], v2 offset:128
	ds_read_b128 v[66:69], v2 offset:192
	ds_read_b128 v[24:27], v2 offset:17536
	ds_read_b128 v[16:19], v2 offset:17600
	v_lshrrev_b32_e32 v50, 4, v134
	v_lshlrev_b32_e32 v49, 2, v50
	v_or_b32_e32 v54, s29, v49
	s_waitcnt lgkmcnt(9)
	v_mfma_f32_16x16x32_bf16 v[40:43], v[28:31], v[40:43], 0
	v_lshl_add_u32 v60, v59, 2, s25
	ds_read_b32 v2, v60
	v_cmp_ge_i32_e32 vcc, v59, v54
	s_waitcnt lgkmcnt(9)
	v_mfma_f32_16x16x32_bf16 v[40:43], v[20:23], v[44:47], v[40:43]
	v_cmp_lt_i32_e64 s[0:1], v59, v54
	v_lshl_add_u32 v3, v54, 2, 0
	s_waitcnt lgkmcnt(4)
	v_mfma_f32_16x16x32_bf16 v[44:47], v[12:15], v[62:65], v[40:43]
	s_waitcnt lgkmcnt(3)
	v_mfma_f32_16x16x32_bf16 v[44:47], v[8:11], v[66:69], v[44:47]
	s_nop 1
	v_mov_b32_e32 v42, 0
	v_mov_b32_e32 v40, 0
	s_and_saveexec_b64 s[2:3], s[0:1]
	s_cbranch_execz .LBB0_318
	v_add_u32_e32 v40, 0x20500, v3
	ds_read_b32 v40, v40
	v_add_u32_e32 v41, 0x20600, v3
	ds_read_b32 v41, v41
	s_waitcnt lgkmcnt(1)
	v_sub_f32_e32 v40, v40, v2
	v_mul_f32_e32 v40, 0x3fb8aa3b, v40
	v_exp_f32_e32 v40, v40
	s_nop 0
	v_mul_f32_e32 v40, v44, v40
	s_waitcnt lgkmcnt(0)
	v_mul_f32_e32 v40, v41, v40
